# MoBA layer1 tile loop: batched LDS fragment reads, 16 MFMAs before barrier1, softmax VALU between barriers (rebalanced segments)
# speedup vs baseline: 1.0142x; 1.0142x over previous
; #define ATT_LAS __attribute__((address_space(3)))
; #define ATT_MFMA(a, b, c) __builtin_amdgcn_mfma_f32_32x32x16_bf16((a), (b), (c), 0, 0, 0)
; __device__ __forceinline__ void qkt(f32x16& p0, f32x16& p1, lds_cptr kb, const bf16x8* qr, const f32x16& z) {
; #pragma unroll
;     for (int d0 = 0; d0 < 4; ++d0) {
;         const bf16x8 b0 = *(const ATT_LAS bf16x8*)(kb + d0 * 2048);
;         const bf16x8 b1 = *(const ATT_LAS bf16x8*)(kb + d0 * 2048 + 512);
;         if (d0 == 0) { p0 = ATT_MFMA(b0, qr[0], z); p1 = ATT_MFMA(b1, qr[0], z); }
;         else { p0 = ATT_MFMA(b0, qr[d0], p0); p1 = ATT_MFMA(b1, qr[d0], p1); } }
; }
; __device__ __forceinline__ void pv(f32x16* o, int vb, bf16x8 pa0, bf16x8 pa1, bf16x8 pa2, bf16x8 pa3) {
; #pragma unroll
;     for (int d0 = 0; d0 < 2; ++d0) { s16x4 lo[4], hi[4];
; #pragma unroll
;         for (int ks = 0; ks < 4; ++ks) {
;             asm volatile("ds_read_b64_tr_b16 %0,%1 offset:%c2" : "=&v"(lo[ks]) : "v"(vb), "i"(d0 * 4096 + ks * 1024) : "memory");
;             asm volatile("ds_read_b64_tr_b16 %0,%1 offset:%c2" : "=&v"(hi[ks]) : "v"(vb), "i"(d0 * 4096 + ks * 1024 + 512) : "memory"); }
;         asm volatile("s_waitcnt lgkmcnt(0)" ::: "memory"); __builtin_amdgcn_sched_barrier(0);
;     ...
;         o[d0] = ATT_MFMA(pa0, ATT_PK(0), o[d0]);
;         o[d0] = ATT_MFMA(pa1, ATT_PK(1), o[d0]);
;         o[d0] = ATT_MFMA(pa2, ATT_PK(2), o[d0]);
;         o[d0] = ATT_MFMA(pa3, ATT_PK(3), o[d0]);
;     ...
;     }
; }
.LBB0_1062:
	s_add_i32 s42, s44, 0x2000
	s_and_b32 s45, s42, 0x6000
	v_add_u32_e32 v133, s45, v130
	s_and_b32 s44, s44, 0x6000
	ds_read_b128 v[154:157], v133
	ds_read_b128 v[158:161], v133 offset:512
	ds_read_b128 v[162:165], v133 offset:2048
	ds_read_b128 v[166:169], v133 offset:2560
	ds_read_b128 v[170:173], v133 offset:4096
	ds_read_b128 v[174:177], v133 offset:4608
	ds_read_b128 v[178:181], v133 offset:6144
	ds_read_b128 v[182:185], v133 offset:6656
	v_add_u32_e32 v218, s44, v132
	ds_read_b64_tr_b16 v[186:187], v218
	ds_read_b64_tr_b16 v[188:189], v218 offset:512
	ds_read_b64_tr_b16 v[190:191], v218 offset:1024
	ds_read_b64_tr_b16 v[192:193], v218 offset:1536
	ds_read_b64_tr_b16 v[194:195], v218 offset:2048
	ds_read_b64_tr_b16 v[196:197], v218 offset:2560
	ds_read_b64_tr_b16 v[198:199], v218 offset:3072
	ds_read_b64_tr_b16 v[200:201], v218 offset:3584
	s_cmp_ge_i32 s34, s31
	s_cselect_b64 s[8:9], -1, 0
	s_cbranch_scc1 .Lmb1_near
	s_lshr_b32 s45, s34, 2
	v_lshrrev_b32_e32 v219, s45, v129
	v_and_b32_e32 v219, 1, v219
	v_cmp_eq_u32_e32 vcc, 1, v219
	s_nop 1
	v_cndmask_b32_e32 v219, v126, v128, vcc
	v_add_f32_e32 v48, v0, v219
	v_add_f32_e32 v49, v1, v219
	v_add_f32_e32 v50, v2, v219
	v_add_f32_e32 v51, v3, v219
	v_add_f32_e32 v52, v4, v219
	v_add_f32_e32 v53, v5, v219
	v_add_f32_e32 v54, v6, v219
	v_add_f32_e32 v55, v7, v219
	v_add_f32_e32 v56, v8, v219
	v_add_f32_e32 v57, v9, v219
	v_add_f32_e32 v58, v10, v219
	v_add_f32_e32 v59, v11, v219
	v_add_f32_e32 v60, v12, v219
	v_add_f32_e32 v61, v13, v219
	v_add_f32_e32 v62, v14, v219
	v_add_f32_e32 v63, v15, v219
	s_branch .Lmb1_qk
.Lmb1_near:
	v_mov_b64_e32 v[48:49], v[0:1]
	v_mov_b64_e32 v[50:51], v[2:3]
	v_mov_b64_e32 v[52:53], v[4:5]
	v_mov_b64_e32 v[54:55], v[6:7]
	v_mov_b64_e32 v[56:57], v[8:9]
	v_mov_b64_e32 v[58:59], v[10:11]
	v_mov_b64_e32 v[60:61], v[12:13]
	v_mov_b64_e32 v[62:63], v[14:15]
.Lmb1_qk:
	s_nop 1
	s_waitcnt lgkmcnt(14)
	v_mfma_f32_32x32x16_bf16 v[64:79], v[154:157], v[92:95], v[48:63]
	v_mfma_f32_32x32x16_bf16 v[48:63], v[158:161], v[92:95], v[48:63]
	s_waitcnt lgkmcnt(12)
	v_mfma_f32_32x32x16_bf16 v[64:79], v[162:165], v[88:91], v[64:79]
	v_mfma_f32_32x32x16_bf16 v[48:63], v[166:169], v[88:91], v[48:63]
	s_waitcnt lgkmcnt(10)
	v_mfma_f32_32x32x16_bf16 v[64:79], v[170:173], v[84:87], v[64:79]
	v_mfma_f32_32x32x16_bf16 v[48:63], v[174:177], v[84:87], v[48:63]
	s_waitcnt lgkmcnt(8)
	v_mfma_f32_32x32x16_bf16 v[64:79], v[178:181], v[80:83], v[64:79]
	v_mfma_f32_32x32x16_bf16 v[48:63], v[182:185], v[80:83], v[48:63]
	ds_read_b64_tr_b16 v[202:203], v218 offset:4096
	ds_read_b64_tr_b16 v[204:205], v218 offset:4608
	ds_read_b64_tr_b16 v[206:207], v218 offset:5120
	ds_read_b64_tr_b16 v[208:209], v218 offset:5632
	ds_read_b64_tr_b16 v[210:211], v218 offset:6144
	ds_read_b64_tr_b16 v[212:213], v218 offset:6656
	ds_read_b64_tr_b16 v[214:215], v218 offset:7168
	ds_read_b64_tr_b16 v[216:217], v218 offset:7680
	s_waitcnt lgkmcnt(14)
	v_mfma_f32_32x32x16_bf16 v[16:31], v[108:111], v[186:189], v[16:31]
	s_waitcnt lgkmcnt(12)
	v_mfma_f32_32x32x16_bf16 v[16:31], v[104:107], v[190:193], v[16:31]
	s_waitcnt lgkmcnt(10)
	v_mfma_f32_32x32x16_bf16 v[16:31], v[100:103], v[194:197], v[16:31]
	s_waitcnt lgkmcnt(8)
	v_mfma_f32_32x32x16_bf16 v[16:31], v[96:99], v[198:201], v[16:31]
	s_waitcnt lgkmcnt(6)
	v_mfma_f32_32x32x16_bf16 v[32:47], v[108:111], v[202:205], v[32:47]
	s_waitcnt lgkmcnt(4)
	v_mfma_f32_32x32x16_bf16 v[32:47], v[104:107], v[206:209], v[32:47]
	s_waitcnt lgkmcnt(2)
	v_mfma_f32_32x32x16_bf16 v[32:47], v[100:103], v[210:213], v[32:47]
	s_waitcnt lgkmcnt(0)
	v_mfma_f32_32x32x16_bf16 v[32:47], v[96:99], v[214:217], v[32:47]
	s_barrier
	s_andn2_b64 vcc, exec, s[8:9]
	s_cbranch_vccnz .Lmb1_exp
	s_lshr_b32 s44, s34, 2
	s_cmp_eq_u32 s44, s91
	s_cselect_b64 s[8:9], -1, 0
	s_lshl_b32 s44, 1, s44
	v_and_b32_e32 v96, s44, v129
	v_cmp_ne_u32_e32 vcc, 0, v96
	s_or_b64 vcc, s[8:9], vcc
	s_nop 0
	v_cndmask_b32_e32 v96, v127, v112, vcc
	v_lshl_add_u32 v96, v96, 2, 0
	v_add_u32_e32 v104, 0x1d000, v96
	ds_read2_b32 v[96:97], v104 offset0:58 offset1:59
	ds_read2_b32 v[98:99], v104 offset0:26 offset1:27
	ds_read2_b32 v[100:101], v104 offset0:56 offset1:57
	s_waitcnt lgkmcnt(2)
	v_pk_add_f32 v[64:65], v[64:65], v[96:97] op_sel:[0,1] op_sel_hi:[1,0]
	ds_read2_b32 v[96:97], v104 offset0:24 offset1:25
	s_waitcnt lgkmcnt(2)
	v_pk_add_f32 v[48:49], v[48:49], v[98:99] op_sel:[0,1] op_sel_hi:[1,0]
	ds_read2_b32 v[98:99], v104 offset0:50 offset1:51
	s_waitcnt lgkmcnt(2)
	v_pk_add_f32 v[66:67], v[66:67], v[100:101] op_sel:[0,1] op_sel_hi:[1,0]
	ds_read2_b32 v[100:101], v104 offset0:18 offset1:19
	s_waitcnt lgkmcnt(1)
	v_pk_add_f32 v[68:69], v[68:69], v[98:99] op_sel:[0,1] op_sel_hi:[1,0]
	ds_read2_b32 v[98:99], v104 offset0:16 offset1:17
	s_waitcnt lgkmcnt(1)
	v_pk_add_f32 v[52:53], v[52:53], v[100:101] op_sel:[0,1] op_sel_hi:[1,0]
	ds_read2_b32 v[100:101], v104 offset0:42 offset1:43
	v_pk_add_f32 v[50:51], v[50:51], v[96:97] op_sel:[0,1] op_sel_hi:[1,0]
	ds_read2_b32 v[96:97], v104 offset0:48 offset1:49
	s_waitcnt lgkmcnt(1)
	v_pk_add_f32 v[72:73], v[72:73], v[100:101] op_sel:[0,1] op_sel_hi:[1,0]
	ds_read2_b32 v[100:101], v104 offset0:8 offset1:9
	s_waitcnt lgkmcnt(1)
	v_pk_add_f32 v[70:71], v[70:71], v[96:97] op_sel:[0,1] op_sel_hi:[1,0]
	ds_read2_b32 v[96:97], v104 offset0:10 offset1:11
	v_pk_add_f32 v[54:55], v[54:55], v[98:99] op_sel:[0,1] op_sel_hi:[1,0]
	ds_read2_b32 v[98:99], v104 offset0:40 offset1:41
	s_waitcnt lgkmcnt(2)
	v_pk_add_f32 v[58:59], v[58:59], v[100:101] op_sel:[0,1] op_sel_hi:[1,0]
	s_waitcnt lgkmcnt(1)
	v_pk_add_f32 v[56:57], v[56:57], v[96:97] op_sel:[0,1] op_sel_hi:[1,0]
	ds_read2_b32 v[96:97], v104 offset0:34 offset1:35
	s_waitcnt lgkmcnt(1)
	v_pk_add_f32 v[74:75], v[74:75], v[98:99] op_sel:[0,1] op_sel_hi:[1,0]
	ds_read2_b32 v[98:99], v104 offset0:2 offset1:3
	ds_read2_b32 v[102:103], v104 offset0:32 offset1:33
	ds_read2_b32 v[104:105], v104 offset1:1
	s_waitcnt lgkmcnt(3)
	v_pk_add_f32 v[76:77], v[76:77], v[96:97] op_sel:[0,1] op_sel_hi:[1,0]
	s_waitcnt lgkmcnt(2)
	v_pk_add_f32 v[60:61], v[60:61], v[98:99] op_sel:[0,1] op_sel_hi:[1,0]
	s_waitcnt lgkmcnt(1)
	v_pk_add_f32 v[78:79], v[78:79], v[102:103] op_sel:[0,1] op_sel_hi:[1,0]
	s_waitcnt lgkmcnt(0)
	v_pk_add_f32 v[62:63], v[62:63], v[104:105] op_sel:[0,1] op_sel_hi:[1,0]
.Lmb1_exp:
	v_exp_f32_e32 v64, v64
	v_exp_f32_e32 v48, v48
	v_exp_f32_e32 v65, v65
	v_exp_f32_e32 v49, v49
	v_exp_f32_e32 v66, v66
	v_exp_f32_e32 v50, v50
	v_exp_f32_e32 v67, v67
	v_exp_f32_e32 v51, v51
	v_add_f32_e32 v96, v48, v64
	v_exp_f32_e32 v68, v68
	v_exp_f32_e32 v52, v52
	v_add_f32_e32 v96, 0, v96
	v_add_f32_e32 v97, v49, v65
	v_exp_f32_e32 v69, v69
	v_exp_f32_e32 v53, v53
	v_add_f32_e32 v96, v97, v96
	v_add_f32_e32 v97, v50, v66
	v_exp_f32_e32 v70, v70
	v_exp_f32_e32 v54, v54
	v_add_f32_e32 v96, v97, v96
	v_add_f32_e32 v97, v51, v67
	v_exp_f32_e32 v71, v71
	v_exp_f32_e32 v55, v55
	v_add_f32_e32 v96, v97, v96
	v_add_f32_e32 v97, v52, v68
	v_exp_f32_e32 v72, v72
	v_exp_f32_e32 v56, v56
	v_add_f32_e32 v96, v97, v96
	v_add_f32_e32 v97, v53, v69
	v_exp_f32_e32 v73, v73
	v_exp_f32_e32 v57, v57
	v_add_f32_e32 v96, v97, v96
	v_add_f32_e32 v97, v54, v70
	v_exp_f32_e32 v74, v74
	v_exp_f32_e32 v58, v58
	v_add_f32_e32 v96, v97, v96
	v_add_f32_e32 v97, v55, v71
	v_exp_f32_e32 v75, v75
	v_exp_f32_e32 v59, v59
	v_add_f32_e32 v96, v97, v96
	v_add_f32_e32 v97, v56, v72
	v_exp_f32_e32 v76, v76
	v_exp_f32_e32 v60, v60
	v_add_f32_e32 v96, v97, v96
	v_add_f32_e32 v97, v57, v73
	v_exp_f32_e32 v77, v77
	v_exp_f32_e32 v61, v61
	v_add_f32_e32 v96, v97, v96
	v_add_f32_e32 v97, v58, v74
	v_exp_f32_e32 v78, v78
	v_exp_f32_e32 v62, v62
	v_add_f32_e32 v96, v97, v96
	v_add_f32_e32 v97, v59, v75
	v_exp_f32_e32 v79, v79
	v_exp_f32_e32 v63, v63
	v_add_f32_e32 v96, v97, v96
	v_add_f32_e32 v97, v60, v76
	v_add_f32_e32 v96, v97, v96
	v_add_f32_e32 v97, v61, v77
	v_add_f32_e32 v96, v97, v96
	v_add_f32_e32 v97, v62, v78
	v_add_f32_e32 v96, v97, v96
	v_add_f32_e32 v97, v63, v79
	v_add_f32_e32 v96, v97, v96
	v_add_f32_e32 v131, v131, v96
	v_cvt_pk_bf16_f32 v108, v64, v65
	v_cvt_pk_bf16_f32 v109, v66, v67
	v_cvt_pk_bf16_f32 v110, v68, v69
	v_cvt_pk_bf16_f32 v111, v70, v71
	v_cvt_pk_bf16_f32 v104, v72, v73
	v_cvt_pk_bf16_f32 v105, v74, v75
	v_cvt_pk_bf16_f32 v106, v76, v77
	v_cvt_pk_bf16_f32 v107, v78, v79
	v_cvt_pk_bf16_f32 v100, v48, v49
	v_cvt_pk_bf16_f32 v101, v50, v51
	v_cvt_pk_bf16_f32 v102, v52, v53
	v_cvt_pk_bf16_f32 v103, v54, v55
	v_cvt_pk_bf16_f32 v96, v56, v57
	v_cvt_pk_bf16_f32 v97, v58, v59
	v_cvt_pk_bf16_f32 v98, v60, v61
	v_cvt_pk_bf16_f32 v99, v62, v63
	v_lshl_add_u64 v[114:115], v[114:115], 0, s[22:23]
	v_subrev_u32_e32 v112, 64, v112
	v_lshl_add_u64 v[116:117], v[116:117], 0, s[22:23]
	s_add_i32 s34, s34, 1
	s_cmp_gt_i32 s43, 1
	s_cbranch_scc1 .Lmb1_w2
	s_cmp_lg_u32 s43, 1
	s_cbranch_scc1 .Lmb1_w0
	s_waitcnt vmcnt(1) lgkmcnt(0)
	s_barrier
	s_branch .Lmb1_bdone
.Lmb1_w0:
	s_waitcnt vmcnt(0) lgkmcnt(0)
	s_barrier
	s_branch .Lmb1_bdone

; template <int MODE> __device__ __forceinline__ void attn_unit(int b, int h, int qb, int t_lo, const bf16_t* Q, const bf16_t* __restrict__ K, const bf16_t* __restrict__ V, bf16_t* O, ATT_LAS unsigned char* lds, const int wid, const float kn2, const float bmax) {
;     ...
; #pragma unroll 1
;     for (int j = 0; j < n - 1; ++j) ATT_ITER(j, true, true);
.Lmb1_bdone:
	s_cmp_lg_u32 s37, s36
	s_cbranch_scc0 .LBB0_1075
	s_mov_b32 s44, s42
	s_add_i32 s37, s34, -1
	s_cmp_ge_u32 s37, s30
	s_mov_b32 s43, 0
	s_cbranch_scc0 .LBB0_1059
	s_branch .LBB0_1060
